# causal band mask in attention band loops rewritten: 2 independent instr per element instead of a 4-instr serial chain
# speedup vs baseline: 1.0053x; 1.0010x over previous
;   #define RESC() do{ if(resc){ asm volatile("s_waitcnt lgkmcnt(0)":::"memory"); \
;       _Pragma("unroll") for(int d_=0;d_<2;++d_) _Pragma("unroll") for(int r=0;r<16;++r)o[d_][r]*=wsf[crow(r,hi)]; } }while(0)
;   #define ROT() do{sl_prev=sl_cur;sl_cur=sl_next;sl_next=(sl_next==(NSLOT-1)*SLOTB)?0:sl_next+SLOTB;}while(0)
;   #define ENDW(tt) do{ if((tt)+3<NT){WAIT_BAR(2);} else if((tt)+2<NT){WAIT_BAR(1);} else {WAIT_BAR(0);} }while(0)
; __device__ __forceinline__ void cmask(f32x16&p0,f32x16&p1,int jb,int qrel,int hi){
;   const float NEG=-INFINITY; int kb=64*jb+4*hi;
;   #pragma unroll
;   for(int r=0;r<16;++r){int kv=kb+(r&3)+8*(r>>2); if(kv>qrel)p0[r]=NEG; if(kv+32>qrel)p1[r]=NEG;}
; }
; template<int THRL,int MODE,int DM,bool DRY=false> __device__ __forceinline__ void attn_unit(int b,int h,int qb,const bf16*Q,const bf16*__restrict__ K,const bf16*__restrict__ V,bf16*O,const bf16*__restrict__ Z,const float*__restrict__ XP,const int*__restrict__ TS,volatile unsigned*lw,unsigned nxt,cha ...
;     ...
;   for(;t+1<NT;t+=2){
;     STEP(pB0,pB1,pA0,pA1,t,(t+3<NT),(t+1<NT),(t+1<NT));       ENDW(t);   RESC(); ROT();
;     STEP(pA0,pA1,pB0,pB1,t+1,(t+4<NT),(t+2<NT),(t+2<NT));     ENDW(t+1); RESC(); ROT();
.LBB0_923:
	s_add_i32 s19, s75, s18
	s_add_i32 s10, s19, 4
	s_cmp_lt_i32 s10, 0
	s_cbranch_scc1 .LBB0_925
	v_sub_u32_e32 v76, v246, v81
	v_cmp_le_i32_e64 vcc, 32, v76
	v_cmp_le_i32_e64 s[98:99], 1, v76
	v_cmp_le_i32_e64 s[100:101], 0, v76
	v_cndmask_b32_e64 v112, v234, v112, vcc
	v_cmp_le_i32_e64 vcc, 33, v76
	v_cndmask_b32_e64 v129, v234, v129, s[98:99]
	v_cmp_le_i32_e64 s[98:99], 2, v76
	v_cndmask_b32_e64 v128, v234, v128, s[100:101]
	v_cmp_le_i32_e64 s[100:101], 34, v76
	v_cndmask_b32_e64 v113, v234, v113, vcc
	v_cmp_le_i32_e64 vcc, 3, v76
	v_cndmask_b32_e64 v130, v234, v130, s[98:99]
	v_cmp_le_i32_e64 s[98:99], 35, v76
	v_cndmask_b32_e64 v114, v234, v114, s[100:101]
	v_cmp_le_i32_e64 s[100:101], 8, v76
	v_cndmask_b32_e64 v131, v234, v131, vcc
	v_cmp_le_i32_e64 vcc, 40, v76
	v_cndmask_b32_e64 v115, v234, v115, s[98:99]
	v_cmp_le_i32_e64 s[98:99], 9, v76
	v_cndmask_b32_e64 v132, v234, v132, s[100:101]
	v_cmp_le_i32_e64 s[100:101], 41, v76
	v_cndmask_b32_e64 v116, v234, v116, vcc
	v_cmp_le_i32_e64 vcc, 10, v76
	v_cndmask_b32_e64 v133, v234, v133, s[98:99]
	v_cmp_le_i32_e64 s[98:99], 42, v76
	v_cndmask_b32_e64 v117, v234, v117, s[100:101]
	v_cmp_le_i32_e64 s[100:101], 11, v76
	v_cndmask_b32_e64 v134, v234, v134, vcc
	v_cmp_le_i32_e64 vcc, 43, v76
	v_cndmask_b32_e64 v118, v234, v118, s[98:99]
	v_cmp_le_i32_e64 s[98:99], 16, v76
	v_cndmask_b32_e64 v135, v234, v135, s[100:101]
	v_cmp_le_i32_e64 s[100:101], 48, v76
	v_cndmask_b32_e64 v119, v234, v119, vcc
	v_cmp_le_i32_e64 vcc, 17, v76
	v_cndmask_b32_e64 v136, v234, v136, s[98:99]
	v_cmp_le_i32_e64 s[98:99], 49, v76
	v_cndmask_b32_e64 v120, v234, v120, s[100:101]
	v_cmp_le_i32_e64 s[100:101], 18, v76
	v_cndmask_b32_e64 v137, v234, v137, vcc
	v_cmp_le_i32_e64 vcc, 50, v76
	v_cndmask_b32_e64 v121, v234, v121, s[98:99]
	v_cmp_le_i32_e64 s[98:99], 19, v76
	v_cndmask_b32_e64 v138, v234, v138, s[100:101]
	v_cmp_le_i32_e64 s[100:101], 51, v76
	v_cndmask_b32_e64 v122, v234, v122, vcc
	v_cmp_le_i32_e64 vcc, 24, v76
	v_cndmask_b32_e64 v139, v234, v139, s[98:99]
	v_cmp_le_i32_e64 s[98:99], 56, v76
	v_cndmask_b32_e64 v123, v234, v123, s[100:101]
	v_cmp_le_i32_e64 s[100:101], 25, v76
	v_cndmask_b32_e64 v140, v234, v140, vcc
	v_cmp_le_i32_e64 vcc, 57, v76
	v_cndmask_b32_e64 v124, v234, v124, s[98:99]
	v_cmp_le_i32_e64 s[98:99], 26, v76
	v_cndmask_b32_e64 v141, v234, v141, s[100:101]
	v_cmp_le_i32_e64 s[100:101], 58, v76
	v_cndmask_b32_e64 v125, v234, v125, vcc
	v_cmp_le_i32_e64 vcc, 27, v76
	v_cndmask_b32_e64 v142, v234, v142, s[98:99]
	v_cmp_le_i32_e64 s[98:99], 59, v76
	v_cndmask_b32_e64 v126, v234, v126, s[100:101]
	v_cndmask_b32_e64 v143, v234, v143, vcc
	v_cndmask_b32_e64 v127, v234, v127, s[98:99]

;   #define RESC() do{ if(resc){ asm volatile("s_waitcnt lgkmcnt(0)":::"memory"); \
;       _Pragma("unroll") for(int d_=0;d_<2;++d_) _Pragma("unroll") for(int r=0;r<16;++r)o[d_][r]*=wsf[crow(r,hi)]; } }while(0)
;   #define ROT() do{sl_prev=sl_cur;sl_cur=sl_next;sl_next=(sl_next==(NSLOT-1)*SLOTB)?0:sl_next+SLOTB;}while(0)
;   #define ENDW(tt) do{ if((tt)+3<NT){WAIT_BAR(2);} else if((tt)+2<NT){WAIT_BAR(1);} else {WAIT_BAR(0);} }while(0)
; __device__ __forceinline__ void cmask(f32x16&p0,f32x16&p1,int jb,int qrel,int hi){
;   const float NEG=-INFINITY; int kb=64*jb+4*hi;
;   #pragma unroll
;   for(int r=0;r<16;++r){int kv=kb+(r&3)+8*(r>>2); if(kv>qrel)p0[r]=NEG; if(kv+32>qrel)p1[r]=NEG;}
; }
; template<int THRL,int MODE,int DM,bool DRY=false> __device__ __forceinline__ void attn_unit(int b,int h,int qb,const bf16*Q,const bf16*__restrict__ K,const bf16*__restrict__ V,bf16*O,const bf16*__restrict__ Z,const float*__restrict__ XP,const int*__restrict__ TS,volatile unsigned*lw,unsigned nxt,cha ...
;     ...
;   for(;t+1<NT;t+=2){
;     STEP(pB0,pB1,pA0,pA1,t,(t+3<NT),(t+1<NT),(t+1<NT));       ENDW(t);   RESC(); ROT();
;     STEP(pA0,pA1,pB0,pB1,t+1,(t+4<NT),(t+2<NT),(t+2<NT));     ENDW(t+1); RESC(); ROT();
.LBB0_935:
	v_sub_u32_e32 v113, v246, v81
	v_subrev_u32_e32 v113, 64, v113
	v_cmp_le_i32_e64 vcc, 32, v113
	v_cmp_le_i32_e64 s[98:99], 1, v113
	v_cmp_le_i32_e64 s[100:101], 0, v113
	v_cndmask_b32_e64 v64, v234, v64, vcc
	v_cmp_le_i32_e64 vcc, 33, v113
	v_cndmask_b32_e64 v97, v234, v97, s[98:99]
	v_cmp_le_i32_e64 s[98:99], 2, v113
	v_cndmask_b32_e64 v96, v234, v96, s[100:101]
	v_cmp_le_i32_e64 s[100:101], 34, v113
	v_cndmask_b32_e64 v65, v234, v65, vcc
	v_cmp_le_i32_e64 vcc, 3, v113
	v_cndmask_b32_e64 v98, v234, v98, s[98:99]
	v_cmp_le_i32_e64 s[98:99], 35, v113
	v_cndmask_b32_e64 v66, v234, v66, s[100:101]
	v_cmp_le_i32_e64 s[100:101], 8, v113
	v_cndmask_b32_e64 v99, v234, v99, vcc
	v_cmp_le_i32_e64 vcc, 40, v113
	v_cndmask_b32_e64 v67, v234, v67, s[98:99]
	v_cmp_le_i32_e64 s[98:99], 9, v113
	v_cndmask_b32_e64 v100, v234, v100, s[100:101]
	v_cmp_le_i32_e64 s[100:101], 41, v113
	v_cndmask_b32_e64 v68, v234, v68, vcc
	v_cmp_le_i32_e64 vcc, 10, v113
	v_cndmask_b32_e64 v101, v234, v101, s[98:99]
	v_cmp_le_i32_e64 s[98:99], 42, v113
	v_cndmask_b32_e64 v69, v234, v69, s[100:101]
	v_cmp_le_i32_e64 s[100:101], 11, v113
	v_cndmask_b32_e64 v102, v234, v102, vcc
	v_cmp_le_i32_e64 vcc, 43, v113
	v_cndmask_b32_e64 v70, v234, v70, s[98:99]
	v_cmp_le_i32_e64 s[98:99], 16, v113
	v_cndmask_b32_e64 v103, v234, v103, s[100:101]
	v_cmp_le_i32_e64 s[100:101], 48, v113
	v_cndmask_b32_e64 v71, v234, v71, vcc
	v_cmp_le_i32_e64 vcc, 17, v113
	v_cndmask_b32_e64 v104, v234, v104, s[98:99]
	v_cmp_le_i32_e64 s[98:99], 49, v113
	v_cndmask_b32_e64 v72, v234, v72, s[100:101]
	v_cmp_le_i32_e64 s[100:101], 18, v113
	v_cndmask_b32_e64 v105, v234, v105, vcc
	v_cmp_le_i32_e64 vcc, 50, v113
	v_cndmask_b32_e64 v73, v234, v73, s[98:99]
	v_cmp_le_i32_e64 s[98:99], 19, v113
	v_cndmask_b32_e64 v106, v234, v106, s[100:101]
	v_cmp_le_i32_e64 s[100:101], 51, v113
	v_cndmask_b32_e64 v74, v234, v74, vcc
	v_cmp_le_i32_e64 vcc, 24, v113
	v_cndmask_b32_e64 v107, v234, v107, s[98:99]
	v_cmp_le_i32_e64 s[98:99], 56, v113
	v_cndmask_b32_e64 v75, v234, v75, s[100:101]
	v_cmp_le_i32_e64 s[100:101], 25, v113
	v_cndmask_b32_e64 v108, v234, v108, vcc
	v_cmp_le_i32_e64 vcc, 57, v113
	v_cndmask_b32_e64 v76, v234, v76, s[98:99]
	v_cmp_le_i32_e64 s[98:99], 26, v113
	v_cndmask_b32_e64 v109, v234, v109, s[100:101]
	v_cmp_le_i32_e64 s[100:101], 58, v113
	v_cndmask_b32_e64 v77, v234, v77, vcc
	v_cmp_le_i32_e64 vcc, 27, v113
	v_cndmask_b32_e64 v110, v234, v110, s[98:99]
	v_cmp_le_i32_e64 s[98:99], 59, v113
	v_cndmask_b32_e64 v78, v234, v78, s[100:101]
	v_cndmask_b32_e64 v111, v234, v111, vcc
	v_cndmask_b32_e64 v79, v234, v79, s[98:99]

; __device__ __forceinline__ void cmask(f32x16&p0,f32x16&p1,int jb,int qrel,int hi){
;   const float NEG=-INFINITY; int kb=64*jb+4*hi;
;   #pragma unroll
;   for(int r=0;r<16;++r){int kv=kb+(r&3)+8*(r>>2); if(kv>qrel)p0[r]=NEG; if(kv+32>qrel)p1[r]=NEG;}
; }
.LBB0_1474:
	v_lshl_add_u64 v[200:201], v[198:199], 0, s[54:55]
	v_lshl_add_u64 v[32:33], v[200:201], 0, s[48:49]
	s_add_i32 s10, s66, s84
	s_mov_b32 s11, m0
	s_mov_b32 m0, s10
	s_nop 0
	global_load_lds_dwordx4 v[32:33], off
	s_mov_b32 m0, s11
	ds_read_b128 v[32:35], v192
	ds_read_b128 v[36:39], v192 offset:32
	ds_read_b128 v[40:43], v192 offset:128
	ds_read_b128 v[44:47], v192 offset:160
	ds_read_b128 v[48:51], v192 offset:64
	ds_read_b128 v[52:55], v192 offset:96
	ds_read_b128 v[128:131], v192 offset:192
	ds_read_b128 v[134:137], v192 offset:224
	s_waitcnt lgkmcnt(7)
	v_pk_add_f32 v[34:35], v[194:195], v[34:35] op_sel_hi:[0,1]
	s_waitcnt lgkmcnt(6)
	v_pk_add_f32 v[38:39], v[194:195], v[38:39] op_sel_hi:[0,1]
	s_waitcnt lgkmcnt(3)
	v_pk_add_f32 v[50:51], v[194:195], v[50:51] op_sel_hi:[0,1]
	s_waitcnt lgkmcnt(2)
	v_pk_add_f32 v[54:55], v[194:195], v[54:55] op_sel_hi:[0,1]
	v_pk_add_f32 v[32:33], v[194:195], v[32:33] op_sel_hi:[0,1]
	v_pk_add_f32 v[36:37], v[194:195], v[36:37] op_sel_hi:[0,1]
	v_pk_add_f32 v[48:49], v[194:195], v[48:49] op_sel_hi:[0,1]
	v_pk_add_f32 v[52:53], v[194:195], v[52:53] op_sel_hi:[0,1]
	s_add_i32 s63, s85, s62
	v_sub_f32_e32 v63, v95, v55
	v_sub_f32_e32 v62, v94, v54
	v_sub_f32_e32 v59, v91, v51
	v_sub_f32_e32 v58, v90, v50
	v_sub_f32_e32 v55, v87, v39
	v_sub_f32_e32 v54, v86, v38
	v_sub_f32_e32 v51, v83, v35
	v_sub_f32_e32 v50, v82, v34
	v_sub_f32_e32 v61, v93, v53
	v_sub_f32_e32 v60, v92, v52
	v_sub_f32_e32 v57, v89, v49
	v_sub_f32_e32 v56, v88, v48
	v_sub_f32_e32 v53, v85, v37
	v_sub_f32_e32 v52, v84, v36
	v_sub_f32_e32 v49, v81, v33
	v_sub_f32_e32 v48, v80, v32
	v_pk_add_f32 v[32:33], v[194:195], v[42:43] op_sel_hi:[0,1]
	v_pk_add_f32 v[34:35], v[194:195], v[46:47] op_sel_hi:[0,1]
	s_waitcnt lgkmcnt(1)
	v_pk_add_f32 v[36:37], v[194:195], v[130:131] op_sel_hi:[0,1]
	s_waitcnt lgkmcnt(0)
	v_pk_add_f32 v[38:39], v[194:195], v[136:137] op_sel_hi:[0,1]
	v_pk_add_f32 v[80:81], v[194:195], v[40:41] op_sel_hi:[0,1]
	v_pk_add_f32 v[82:83], v[194:195], v[44:45] op_sel_hi:[0,1]
	v_pk_add_f32 v[40:41], v[194:195], v[128:129] op_sel_hi:[0,1]
	v_pk_add_f32 v[44:45], v[194:195], v[134:135] op_sel_hi:[0,1]
	s_add_i32 s10, s63, 2
	v_sub_f32_e32 v47, v79, v39
	v_sub_f32_e32 v46, v78, v38
	v_sub_f32_e32 v43, v75, v37
	v_sub_f32_e32 v42, v74, v36
	v_sub_f32_e32 v39, v71, v35
	v_sub_f32_e32 v38, v70, v34
	v_sub_f32_e32 v35, v67, v33
	v_sub_f32_e32 v34, v66, v32
	v_sub_f32_e32 v45, v77, v45
	v_sub_f32_e32 v44, v76, v44
	v_sub_f32_e32 v41, v73, v41
	v_sub_f32_e32 v40, v72, v40
	v_sub_f32_e32 v37, v69, v83
	v_sub_f32_e32 v36, v68, v82
	v_sub_f32_e32 v33, v65, v81
	s_cmp_lt_i32 s10, 0
	v_sub_f32_e32 v32, v64, v80
	s_cbranch_scc1 .LBB0_1476
	v_sub_u32_e32 v64, v214, v224
	v_cmp_le_i32_e64 vcc, 32, v64
	v_cmp_le_i32_e64 s[98:99], 1, v64
	v_cmp_le_i32_e64 s[100:101], 0, v64
	v_cndmask_b32_e64 v32, v205, v32, vcc
	v_cmp_le_i32_e64 vcc, 33, v64
	v_cndmask_b32_e64 v49, v205, v49, s[98:99]
	v_cmp_le_i32_e64 s[98:99], 2, v64
	v_cndmask_b32_e64 v48, v205, v48, s[100:101]
	v_cmp_le_i32_e64 s[100:101], 34, v64
	v_cndmask_b32_e64 v33, v205, v33, vcc
	v_cmp_le_i32_e64 vcc, 3, v64
	v_cndmask_b32_e64 v50, v205, v50, s[98:99]
	v_cmp_le_i32_e64 s[98:99], 35, v64
	v_cndmask_b32_e64 v34, v205, v34, s[100:101]
	v_cmp_le_i32_e64 s[100:101], 8, v64
	v_cndmask_b32_e64 v51, v205, v51, vcc
	v_cmp_le_i32_e64 vcc, 40, v64
	v_cndmask_b32_e64 v35, v205, v35, s[98:99]
	v_cmp_le_i32_e64 s[98:99], 9, v64
	v_cndmask_b32_e64 v52, v205, v52, s[100:101]
	v_cmp_le_i32_e64 s[100:101], 41, v64
	v_cndmask_b32_e64 v36, v205, v36, vcc
	v_cmp_le_i32_e64 vcc, 10, v64
	v_cndmask_b32_e64 v53, v205, v53, s[98:99]
	v_cmp_le_i32_e64 s[98:99], 42, v64
	v_cndmask_b32_e64 v37, v205, v37, s[100:101]
	v_cmp_le_i32_e64 s[100:101], 11, v64
	v_cndmask_b32_e64 v54, v205, v54, vcc
	v_cmp_le_i32_e64 vcc, 43, v64
	v_cndmask_b32_e64 v38, v205, v38, s[98:99]
	v_cmp_le_i32_e64 s[98:99], 16, v64
	v_cndmask_b32_e64 v55, v205, v55, s[100:101]
	v_cmp_le_i32_e64 s[100:101], 48, v64
	v_cndmask_b32_e64 v39, v205, v39, vcc
	v_cmp_le_i32_e64 vcc, 17, v64
	v_cndmask_b32_e64 v56, v205, v56, s[98:99]
	v_cmp_le_i32_e64 s[98:99], 49, v64
	v_cndmask_b32_e64 v40, v205, v40, s[100:101]
	v_cmp_le_i32_e64 s[100:101], 18, v64
	v_cndmask_b32_e64 v57, v205, v57, vcc
	v_cmp_le_i32_e64 vcc, 50, v64
	v_cndmask_b32_e64 v41, v205, v41, s[98:99]
	v_cmp_le_i32_e64 s[98:99], 19, v64
	v_cndmask_b32_e64 v58, v205, v58, s[100:101]
	v_cmp_le_i32_e64 s[100:101], 51, v64
	v_cndmask_b32_e64 v42, v205, v42, vcc
	v_cmp_le_i32_e64 vcc, 24, v64
	v_cndmask_b32_e64 v59, v205, v59, s[98:99]
	v_cmp_le_i32_e64 s[98:99], 56, v64
	v_cndmask_b32_e64 v43, v205, v43, s[100:101]
	v_cmp_le_i32_e64 s[100:101], 25, v64
	v_cndmask_b32_e64 v60, v205, v60, vcc
	v_cmp_le_i32_e64 vcc, 57, v64
	v_cndmask_b32_e64 v44, v205, v44, s[98:99]
	v_cmp_le_i32_e64 s[98:99], 26, v64
	v_cndmask_b32_e64 v61, v205, v61, s[100:101]
	v_cmp_le_i32_e64 s[100:101], 58, v64
	v_cndmask_b32_e64 v45, v205, v45, vcc
	v_cmp_le_i32_e64 vcc, 27, v64
	v_cndmask_b32_e64 v62, v205, v62, s[98:99]
	v_cmp_le_i32_e64 s[98:99], 59, v64
	v_cndmask_b32_e64 v46, v205, v46, s[100:101]
	v_cndmask_b32_e64 v63, v205, v63, vcc
	v_cndmask_b32_e64 v47, v205, v47, s[98:99]

; __device__ __forceinline__ void cmask(f32x16&p0,f32x16&p1,int jb,int qrel,int hi){
;   const float NEG=-INFINITY; int kb=64*jb+4*hi;
;   #pragma unroll
;   for(int r=0;r<16;++r){int kv=kb+(r&3)+8*(r>>2); if(kv>qrel)p0[r]=NEG; if(kv+32>qrel)p1[r]=NEG;}
; }
.LBB0_1485:
	ds_read_b128 v[32:35], v192 offset:256
	ds_read_b128 v[36:39], v192 offset:288
	ds_read_b128 v[40:43], v192 offset:384
	ds_read_b128 v[44:47], v192 offset:416
	ds_read_b128 v[48:51], v192 offset:320
	ds_read_b128 v[52:55], v192 offset:352
	ds_read_b128 v[200:203], v192 offset:448
	ds_read_b128 v[228:231], v192 offset:480
	s_waitcnt lgkmcnt(7)
	v_pk_add_f32 v[34:35], v[194:195], v[34:35] op_sel_hi:[0,1]
	s_waitcnt lgkmcnt(6)
	v_pk_add_f32 v[38:39], v[194:195], v[38:39] op_sel_hi:[0,1]
	s_waitcnt lgkmcnt(3)
	v_pk_add_f32 v[50:51], v[194:195], v[50:51] op_sel_hi:[0,1]
	s_waitcnt lgkmcnt(2)
	v_pk_add_f32 v[54:55], v[194:195], v[54:55] op_sel_hi:[0,1]
	v_pk_add_f32 v[32:33], v[194:195], v[32:33] op_sel_hi:[0,1]
	v_pk_add_f32 v[36:37], v[194:195], v[36:37] op_sel_hi:[0,1]
	v_pk_add_f32 v[48:49], v[194:195], v[48:49] op_sel_hi:[0,1]
	v_pk_add_f32 v[52:53], v[194:195], v[52:53] op_sel_hi:[0,1]
	v_sub_f32_e32 v63, v95, v55
	v_sub_f32_e32 v62, v94, v54
	v_sub_f32_e32 v59, v91, v51
	v_sub_f32_e32 v58, v90, v50
	v_sub_f32_e32 v55, v87, v39
	v_sub_f32_e32 v54, v86, v38
	v_sub_f32_e32 v51, v83, v35
	v_sub_f32_e32 v50, v82, v34
	v_sub_f32_e32 v61, v93, v53
	v_sub_f32_e32 v60, v92, v52
	v_sub_f32_e32 v57, v89, v49
	v_sub_f32_e32 v56, v88, v48
	v_sub_f32_e32 v53, v85, v37
	v_sub_f32_e32 v52, v84, v36
	v_sub_f32_e32 v49, v81, v33
	v_sub_f32_e32 v48, v80, v32
	v_pk_add_f32 v[32:33], v[194:195], v[42:43] op_sel_hi:[0,1]
	v_pk_add_f32 v[34:35], v[194:195], v[46:47] op_sel_hi:[0,1]
	s_waitcnt lgkmcnt(1)
	v_pk_add_f32 v[36:37], v[194:195], v[202:203] op_sel_hi:[0,1]
	s_waitcnt lgkmcnt(0)
	v_pk_add_f32 v[38:39], v[194:195], v[230:231] op_sel_hi:[0,1]
	v_pk_add_f32 v[80:81], v[194:195], v[40:41] op_sel_hi:[0,1]
	v_pk_add_f32 v[82:83], v[194:195], v[44:45] op_sel_hi:[0,1]
	v_pk_add_f32 v[40:41], v[194:195], v[200:201] op_sel_hi:[0,1]
	v_pk_add_f32 v[44:45], v[194:195], v[228:229] op_sel_hi:[0,1]
	s_add_i32 s63, s63, 3
	v_sub_f32_e32 v47, v79, v39
	v_sub_f32_e32 v46, v78, v38
	v_sub_f32_e32 v43, v75, v37
	v_sub_f32_e32 v42, v74, v36
	v_sub_f32_e32 v39, v71, v35
	v_sub_f32_e32 v38, v70, v34
	v_sub_f32_e32 v35, v67, v33
	v_sub_f32_e32 v34, v66, v32
	v_sub_f32_e32 v45, v77, v45
	v_sub_f32_e32 v44, v76, v44
	v_sub_f32_e32 v41, v73, v41
	v_sub_f32_e32 v40, v72, v40
	v_sub_f32_e32 v37, v69, v83
	v_sub_f32_e32 v36, v68, v82
	v_sub_f32_e32 v33, v65, v81
	s_cmp_lt_i32 s63, 0
	v_sub_f32_e32 v32, v64, v80
	s_cbranch_scc1 .LBB0_1487
	v_sub_u32_e32 v65, v214, v224
	v_subrev_u32_e32 v65, 64, v65
	v_cmp_le_i32_e64 vcc, 32, v65
	v_cmp_le_i32_e64 s[98:99], 1, v65
	v_cmp_le_i32_e64 s[100:101], 0, v65
	v_cndmask_b32_e64 v32, v205, v32, vcc
	v_cmp_le_i32_e64 vcc, 33, v65
	v_cndmask_b32_e64 v49, v205, v49, s[98:99]
	v_cmp_le_i32_e64 s[98:99], 2, v65
	v_cndmask_b32_e64 v48, v205, v48, s[100:101]
	v_cmp_le_i32_e64 s[100:101], 34, v65
	v_cndmask_b32_e64 v33, v205, v33, vcc
	v_cmp_le_i32_e64 vcc, 3, v65
	v_cndmask_b32_e64 v50, v205, v50, s[98:99]
	v_cmp_le_i32_e64 s[98:99], 35, v65
	v_cndmask_b32_e64 v34, v205, v34, s[100:101]
	v_cmp_le_i32_e64 s[100:101], 8, v65
	v_cndmask_b32_e64 v51, v205, v51, vcc
	v_cmp_le_i32_e64 vcc, 40, v65
	v_cndmask_b32_e64 v35, v205, v35, s[98:99]
	v_cmp_le_i32_e64 s[98:99], 9, v65
	v_cndmask_b32_e64 v52, v205, v52, s[100:101]
	v_cmp_le_i32_e64 s[100:101], 41, v65
	v_cndmask_b32_e64 v36, v205, v36, vcc
	v_cmp_le_i32_e64 vcc, 10, v65
	v_cndmask_b32_e64 v53, v205, v53, s[98:99]
	v_cmp_le_i32_e64 s[98:99], 42, v65
	v_cndmask_b32_e64 v37, v205, v37, s[100:101]
	v_cmp_le_i32_e64 s[100:101], 11, v65
	v_cndmask_b32_e64 v54, v205, v54, vcc
	v_cmp_le_i32_e64 vcc, 43, v65
	v_cndmask_b32_e64 v38, v205, v38, s[98:99]
	v_cmp_le_i32_e64 s[98:99], 16, v65
	v_cndmask_b32_e64 v55, v205, v55, s[100:101]
	v_cmp_le_i32_e64 s[100:101], 48, v65
	v_cndmask_b32_e64 v39, v205, v39, vcc
	v_cmp_le_i32_e64 vcc, 17, v65
	v_cndmask_b32_e64 v56, v205, v56, s[98:99]
	v_cmp_le_i32_e64 s[98:99], 49, v65
	v_cndmask_b32_e64 v40, v205, v40, s[100:101]
	v_cmp_le_i32_e64 s[100:101], 18, v65
	v_cndmask_b32_e64 v57, v205, v57, vcc
	v_cmp_le_i32_e64 vcc, 50, v65
	v_cndmask_b32_e64 v41, v205, v41, s[98:99]
	v_cmp_le_i32_e64 s[98:99], 19, v65
	v_cndmask_b32_e64 v58, v205, v58, s[100:101]
	v_cmp_le_i32_e64 s[100:101], 51, v65
	v_cndmask_b32_e64 v42, v205, v42, vcc
	v_cmp_le_i32_e64 vcc, 24, v65
	v_cndmask_b32_e64 v59, v205, v59, s[98:99]
	v_cmp_le_i32_e64 s[98:99], 56, v65
	v_cndmask_b32_e64 v43, v205, v43, s[100:101]
	v_cmp_le_i32_e64 s[100:101], 25, v65
	v_cndmask_b32_e64 v60, v205, v60, vcc
	v_cmp_le_i32_e64 vcc, 57, v65
	v_cndmask_b32_e64 v44, v205, v44, s[98:99]
	v_cmp_le_i32_e64 s[98:99], 26, v65
	v_cndmask_b32_e64 v61, v205, v61, s[100:101]
	v_cmp_le_i32_e64 s[100:101], 58, v65
	v_cndmask_b32_e64 v45, v205, v45, vcc
	v_cmp_le_i32_e64 vcc, 27, v65
	v_cndmask_b32_e64 v62, v205, v62, s[98:99]
	v_cmp_le_i32_e64 s[98:99], 59, v65
	v_cndmask_b32_e64 v46, v205, v46, s[100:101]
	v_cndmask_b32_e64 v63, v205, v63, vcc
	v_cndmask_b32_e64 v47, v205, v47, s[98:99]
